# stack + accumulator zeroing no longer waits for the prologue LDS-DMA (9 GEMM prologues)
# speedup vs baseline: 1.0196x; 1.0029x over previous
; template <bool SW>
; __device__ __forceinline__ void gemm_mainloop(const bf16_t* __restrict__ A, int lda, const bf16_t* __restrict__ Bt, int ldb, int K,
;                                               f32x16 (&acc)[2][2], char* lds, int kstart) {
;   const int tid = threadIdx.x, lane = tid & 63, wid = tid >> 6;
;   const int wr = wid >> 1, wc = wid & 1, l31 = lane & 31, hh = lane >> 5;
;   const int lrow = wid * 32 + (lane >> 3);
;   const int nk = K >> 6;
;   kstart &= (nk - 1);
;   const bf16_t* ap[4]; const bf16_t* bp[4];
; #pragma unroll
;   for (int i = 0; i < 4; ++i) {
;     const int row = lrow + 8 * i; const int ch = (lane & 7) ^ ((row >> 1) & 7);
;     ap[i] = A + (size_t)row * lda + ch * 8; bp[i] = Bt + (size_t)row * ldb + ch * 8;
;   }
;   char* ldst = lds + (wid * 32) * 128 + lane * 16;
; #pragma unroll
;   for (int i = 0; i < 4; ++i) { glds16(ap[i] + kstart * 64, ldst + i * 1024); glds16(bp[i] + kstart * 64, ldst + 16384 + i * 1024); }
;   asm volatile("s_waitcnt vmcnt(0)" ::: "memory");
;   __syncthreads();
.LBB0_172:
	s_andn2_b64 vcc, exec, s[0:1]
	s_mov_b32 s34, 2
	s_cbranch_vccnz .LBB0_277
	s_lshl_b32 s53, s52, 7
	s_lshl_b32 s54, s51, 7
	s_cmpk_gt_i32 s52, 0xff
	s_cselect_b64 s[38:39], -1, 0
	s_and_b32 s2, s51, -8
	s_mul_i32 s0, s52, 0x44000
	s_mul_hi_i32 s1, s53, 0x880
	s_add_u32 s0, s33, s0
	s_addc_u32 s1, s27, s1
	s_add_i32 s3, s51, s52
	v_lshl_add_u64 v[0:1], s[0:1], 0, v[64:65]
	v_mov_b32_e32 v109, v65
	s_lshl_b32 s55, s3, 7
	v_lshl_add_u64 v[116:117], v[0:1], 0, v[108:109]
	v_lshl_add_u64 v[0:1], v[66:67], 1, s[0:1]
	v_mov_b32_e32 v111, v65
	s_and_b32 s3, s55, 0x380
	v_lshl_add_u64 v[118:119], v[0:1], 0, v[110:111]
	v_lshl_add_u64 v[0:1], v[68:69], 1, s[0:1]
	s_lshl_b32 s46, s3, 1
	v_lshl_add_u64 v[120:121], v[0:1], 0, v[108:109]
	v_lshl_add_u64 v[0:1], v[70:71], 1, s[0:1]
	s_mov_b32 s47, s77
	v_readfirstlane_b32 s0, v147
	v_lshl_add_u64 v[122:123], v[0:1], 0, v[110:111]
	v_lshl_add_u64 v[0:1], v[116:117], 0, s[46:47]
	s_mov_b32 m0, s0
	s_cmp_lg_u32 s2, 16
	global_load_lds_dwordx4 v[0:1], off
	v_lshl_add_u64 v[128:129], v[118:119], 0, s[46:47]
	v_lshl_add_u64 v[126:127], v[120:121], 0, s[46:47]
	v_lshl_add_u64 v[124:125], v[122:123], 0, s[46:47]
	s_mov_b64 s[0:1], -1
	s_cbranch_scc0 .LBB0_261
	s_mul_i32 s0, s54, 0x880
	s_mul_hi_i32 s1, s54, 0x880
	s_add_u32 s0, s96, s0
	s_addc_u32 s1, s97, s1
	v_lshl_add_u64 v[0:1], s[0:1], 0, v[64:65]
	v_lshl_add_u64 v[130:131], v[0:1], 0, v[108:109]
	v_lshl_add_u64 v[0:1], v[66:67], 1, s[0:1]
	v_lshl_add_u64 v[132:133], v[0:1], 0, v[110:111]
	v_lshl_add_u64 v[0:1], v[68:69], 1, s[0:1]
	v_lshl_add_u64 v[134:135], v[0:1], 0, v[108:109]
	v_lshl_add_u64 v[0:1], v[70:71], 1, s[0:1]
	v_readfirstlane_b32 s0, v156
	v_lshl_add_u64 v[136:137], v[0:1], 0, v[110:111]
	v_lshl_add_u64 v[0:1], v[130:131], 0, s[46:47]
	s_mov_b32 m0, s0
	v_readfirstlane_b32 s0, v157
	global_load_lds_dwordx4 v[0:1], off
	s_mov_b32 m0, s0
	v_readfirstlane_b32 s0, v158
	global_load_lds_dwordx4 v[128:129], off
	v_lshl_add_u64 v[0:1], v[132:133], 0, s[46:47]
	s_mov_b32 m0, s0
	v_readfirstlane_b32 s0, v159
	global_load_lds_dwordx4 v[0:1], off
	s_mov_b32 m0, s0
	v_readfirstlane_b32 s0, v160
	global_load_lds_dwordx4 v[126:127], off
	v_lshl_add_u64 v[0:1], v[134:135], 0, s[46:47]
	s_mov_b32 m0, s0
	v_readfirstlane_b32 s0, v161
	global_load_lds_dwordx4 v[0:1], off
	s_mov_b32 m0, s0
	v_readfirstlane_b32 s0, v162
	global_load_lds_dwordx4 v[124:125], off
	v_lshl_add_u64 v[0:1], v[136:137], 0, s[46:47]
	s_mov_b32 m0, s0
	s_add_i32 s2, s55, 64
	global_load_lds_dwordx4 v[0:1], off
	v_mov_b32_e32 v0, 0
	s_mov_b32 s34, 0
	s_mov_b32 s3, 0
	v_mov_b32_e32 v1, v0
	v_mov_b32_e32 v2, v0
	v_mov_b32_e32 v3, v0
	v_mov_b32_e32 v4, v0
	v_mov_b32_e32 v5, v0
	v_mov_b32_e32 v6, v0
	v_mov_b32_e32 v7, v0
	v_mov_b32_e32 v8, v0
	v_mov_b32_e32 v9, v0
	v_mov_b32_e32 v10, v0
	v_mov_b32_e32 v11, v0
	v_mov_b32_e32 v12, v0
	v_mov_b32_e32 v13, v0
	v_mov_b32_e32 v14, v0
	v_mov_b32_e32 v15, v0
	v_mov_b32_e32 v16, v0
	v_mov_b32_e32 v17, v0
	v_mov_b32_e32 v18, v0
	v_mov_b32_e32 v19, v0
	v_mov_b32_e32 v20, v0
	v_mov_b32_e32 v21, v0
	v_mov_b32_e32 v22, v0
	v_mov_b32_e32 v23, v0
	v_mov_b32_e32 v24, v0
	v_mov_b32_e32 v25, v0
	v_mov_b32_e32 v26, v0
	v_mov_b32_e32 v27, v0
	v_mov_b32_e32 v28, v0
	v_mov_b32_e32 v29, v0
	v_mov_b32_e32 v30, v0
	v_mov_b32_e32 v31, v0
	v_mov_b32_e32 v32, v0
	v_mov_b32_e32 v33, v0
	v_mov_b32_e32 v34, v0
	v_mov_b32_e32 v35, v0
	v_mov_b32_e32 v36, v0
	v_mov_b32_e32 v37, v0
	v_mov_b32_e32 v38, v0
	v_mov_b32_e32 v39, v0
	v_mov_b32_e32 v40, v0
	v_mov_b32_e32 v41, v0
	v_mov_b32_e32 v42, v0
	v_mov_b32_e32 v43, v0
	v_mov_b32_e32 v44, v0
	v_mov_b32_e32 v45, v0
	v_mov_b32_e32 v46, v0
	v_mov_b32_e32 v47, v0
	v_mov_b32_e32 v48, v0
	v_mov_b32_e32 v49, v0
	v_mov_b32_e32 v50, v0
	v_mov_b32_e32 v51, v0
	v_mov_b32_e32 v52, v0
	v_mov_b32_e32 v53, v0
	v_mov_b32_e32 v54, v0
	v_mov_b32_e32 v55, v0
	v_mov_b32_e32 v56, v0
	v_mov_b32_e32 v57, v0
	v_mov_b32_e32 v58, v0
	v_mov_b32_e32 v59, v0
	v_mov_b32_e32 v60, v0
	v_mov_b32_e32 v61, v0
	v_mov_b32_e32 v62, v0
	v_mov_b32_e32 v63, v0
	s_waitcnt vmcnt(0) lgkmcnt(0)
	s_barrier
	s_branch .LBB0_176

; template <bool SW>
; __device__ __forceinline__ void gemm_mainloop(const bf16_t* __restrict__ A, int lda, const bf16_t* __restrict__ Bt, int ldb, int K,
;                                               f32x16 (&acc)[2][2], char* lds, int kstart) {
;   const int tid = threadIdx.x, lane = tid & 63, wid = tid >> 6;
;   const int wr = wid >> 1, wc = wid & 1, l31 = lane & 31, hh = lane >> 5;
;   const int lrow = wid * 32 + (lane >> 3);
;   const int nk = K >> 6;
;   kstart &= (nk - 1);
;   const bf16_t* ap[4]; const bf16_t* bp[4];
; #pragma unroll
;   for (int i = 0; i < 4; ++i) {
;     const int row = lrow + 8 * i; const int ch = (lane & 7) ^ ((row >> 1) & 7);
;     ap[i] = A + (size_t)row * lda + ch * 8; bp[i] = Bt + (size_t)row * ldb + ch * 8;
;   }
;   char* ldst = lds + (wid * 32) * 128 + lane * 16;
; #pragma unroll
;   for (int i = 0; i < 4; ++i) { glds16(ap[i] + kstart * 64, ldst + i * 1024); glds16(bp[i] + kstart * 64, ldst + 16384 + i * 1024); }
;   asm volatile("s_waitcnt vmcnt(0)" ::: "memory");
;   __syncthreads();
.LBB0_261:
	s_mov_b32 s34, 0
	s_and_b64 vcc, exec, s[0:1]
	s_cbranch_vccz .LBB0_277
	s_mul_i32 s0, s51, 0x44000
	s_add_u32 s0, s96, s0
	s_addc_u32 s1, s97, 0
	v_lshl_add_u64 v[0:1], s[0:1], 0, v[64:65]
	v_mov_b32_e32 v109, v65
	v_lshl_add_u64 v[130:131], v[0:1], 0, v[108:109]
	v_lshl_add_u64 v[0:1], v[66:67], 1, s[0:1]
	v_mov_b32_e32 v111, v65
	v_lshl_add_u64 v[132:133], v[0:1], 0, v[110:111]
	v_lshl_add_u64 v[0:1], v[68:69], 1, s[0:1]
	v_lshl_add_u64 v[134:135], v[0:1], 0, v[108:109]
	v_lshl_add_u64 v[0:1], v[70:71], 1, s[0:1]
	s_mov_b32 s47, s77
	v_readfirstlane_b32 s0, v156
	v_lshl_add_u64 v[136:137], v[0:1], 0, v[110:111]
	v_lshl_add_u64 v[0:1], v[130:131], 0, s[46:47]
	s_mov_b32 m0, s0
	v_readfirstlane_b32 s0, v157
	global_load_lds_dwordx4 v[0:1], off
	s_mov_b32 m0, s0
	v_readfirstlane_b32 s0, v158
	global_load_lds_dwordx4 v[128:129], off
	v_lshl_add_u64 v[0:1], v[132:133], 0, s[46:47]
	s_mov_b32 m0, s0
	v_readfirstlane_b32 s0, v159
	global_load_lds_dwordx4 v[0:1], off
	s_mov_b32 m0, s0
	v_readfirstlane_b32 s0, v160
	global_load_lds_dwordx4 v[126:127], off
	v_lshl_add_u64 v[0:1], v[134:135], 0, s[46:47]
	s_mov_b32 m0, s0
	v_readfirstlane_b32 s0, v161
	global_load_lds_dwordx4 v[0:1], off
	s_mov_b32 m0, s0
	v_readfirstlane_b32 s0, v162
	global_load_lds_dwordx4 v[124:125], off
	v_lshl_add_u64 v[0:1], v[136:137], 0, s[46:47]
	s_mov_b32 m0, s0
	s_add_i32 s2, s55, 64
	global_load_lds_dwordx4 v[0:1], off
	v_mov_b32_e32 v0, 0
	s_mov_b32 s3, 0
	v_mov_b32_e32 v1, v0
	v_mov_b32_e32 v2, v0
	v_mov_b32_e32 v3, v0
	v_mov_b32_e32 v4, v0
	v_mov_b32_e32 v5, v0
	v_mov_b32_e32 v6, v0
	v_mov_b32_e32 v7, v0
	v_mov_b32_e32 v8, v0
	v_mov_b32_e32 v9, v0
	v_mov_b32_e32 v10, v0
	v_mov_b32_e32 v11, v0
	v_mov_b32_e32 v12, v0
	v_mov_b32_e32 v13, v0
	v_mov_b32_e32 v14, v0
	v_mov_b32_e32 v15, v0
	v_mov_b32_e32 v16, v0
	v_mov_b32_e32 v17, v0
	v_mov_b32_e32 v18, v0
	v_mov_b32_e32 v19, v0
	v_mov_b32_e32 v20, v0
	v_mov_b32_e32 v21, v0
	v_mov_b32_e32 v22, v0
	v_mov_b32_e32 v23, v0
	v_mov_b32_e32 v24, v0
	v_mov_b32_e32 v25, v0
	v_mov_b32_e32 v26, v0
	v_mov_b32_e32 v27, v0
	v_mov_b32_e32 v28, v0
	v_mov_b32_e32 v29, v0
	v_mov_b32_e32 v30, v0
	v_mov_b32_e32 v31, v0
	v_mov_b32_e32 v32, v0
	v_mov_b32_e32 v33, v0
	v_mov_b32_e32 v34, v0
	v_mov_b32_e32 v35, v0
	v_mov_b32_e32 v36, v0
	v_mov_b32_e32 v37, v0
	v_mov_b32_e32 v38, v0
	v_mov_b32_e32 v39, v0
	v_mov_b32_e32 v40, v0
	v_mov_b32_e32 v41, v0
	v_mov_b32_e32 v42, v0
	v_mov_b32_e32 v43, v0
	v_mov_b32_e32 v44, v0
	v_mov_b32_e32 v45, v0
	v_mov_b32_e32 v46, v0
	v_mov_b32_e32 v47, v0
	v_mov_b32_e32 v48, v0
	v_mov_b32_e32 v49, v0
	v_mov_b32_e32 v50, v0
	v_mov_b32_e32 v51, v0
	v_mov_b32_e32 v52, v0
	v_mov_b32_e32 v53, v0
	v_mov_b32_e32 v54, v0
	v_mov_b32_e32 v55, v0
	v_mov_b32_e32 v56, v0
	v_mov_b32_e32 v57, v0
	v_mov_b32_e32 v58, v0
	v_mov_b32_e32 v59, v0
	v_mov_b32_e32 v60, v0
	v_mov_b32_e32 v61, v0
	v_mov_b32_e32 v62, v0
	v_mov_b32_e32 v63, v0
	s_waitcnt vmcnt(0) lgkmcnt(0)
	s_barrier
	s_branch .LBB0_264

; template <bool SW>
; __device__ __forceinline__ void gemm_mainloop(const bf16_t* __restrict__ A, int lda, const bf16_t* __restrict__ Bt, int ldb, int K,
;                                               f32x16 (&acc)[2][2], char* lds, int kstart) {
;   const int tid = threadIdx.x, lane = tid & 63, wid = tid >> 6;
;   const int wr = wid >> 1, wc = wid & 1, l31 = lane & 31, hh = lane >> 5;
;   const int lrow = wid * 32 + (lane >> 3);
;   const int nk = K >> 6;
;   kstart &= (nk - 1);
;   const bf16_t* ap[4]; const bf16_t* bp[4];
; #pragma unroll
;   for (int i = 0; i < 4; ++i) {
;     const int row = lrow + 8 * i; const int ch = (lane & 7) ^ ((row >> 1) & 7);
;     ap[i] = A + (size_t)row * lda + ch * 8; bp[i] = Bt + (size_t)row * ldb + ch * 8;
;   }
;   char* ldst = lds + (wid * 32) * 128 + lane * 16;
; #pragma unroll
;   for (int i = 0; i < 4; ++i) { glds16(ap[i] + kstart * 64, ldst + i * 1024); glds16(bp[i] + kstart * 64, ldst + 16384 + i * 1024); }
;   asm volatile("s_waitcnt vmcnt(0)" ::: "memory");
;   __syncthreads();
; __device__ void phase_mla_expand(const Params& p, char* lds) {
;     ...
;     } else if (nt < 8) {
;       gemm_mainloop<true>((const bf16_t*)(ws + W_G) + (size_t)m0 * LDK, LDK, (const bf16_t*)(ws + W_WUKV) + (size_t)n0 * LDK, LDK, 128, acc, lds, 2 * ((mt + nt) & 7));
; #pragma unroll
;       for (int i = 0; i < 2; ++i)
; #pragma unroll
;         for (int j = 0; j < 2; ++j) {
;           const int row = m0 + wr * 64 + i * 32 + l31; const int cb = n0 + wc * 64 + j * 32;
;           st_bf16_sw((bf16_t*)(ws + W_D) + (size_t)row * LDH + cb, acc[i][j], hh, 1.f);
;         }
;     } else {
;       gemm_mainloop<false>((const bf16_t*)(ws + W_G) + (size_t)m0 * LDK, LDK, (const bf16_t*)(ws + W_WUKV) + (size_t)n0 * LDK, LDK, 128, acc, lds, 2 * ((mt + nt) & 7));
.LBB0_542:
	s_lshl_b32 s38, s42, 7
	s_lshl_b32 s39, s41, 7
	s_and_b64 vcc, exec, s[0:1]
	s_cbranch_vccz .LBB0_560
	s_mul_i32 s0, s38, 0x140
	s_mul_hi_i32 s1, s38, 0x140
	s_add_u32 s0, s28, s0
	s_addc_u32 s1, s29, s1
	v_lshl_add_u64 v[0:1], s[0:1], 0, v[64:65]
	v_mov_b32_e32 v85, v65
	v_readfirstlane_b32 s2, v114
	v_lshl_add_u64 v[0:1], v[0:1], 0, v[84:85]
	s_mov_b32 m0, s2
	v_lshl_add_u64 v[2:3], v[66:67], 1, s[0:1]
	global_load_lds_dwordx4 v[0:1], off
	v_mov_b32_e32 v87, v65
	v_lshl_add_u64 v[104:105], v[2:3], 0, v[86:87]
	v_lshl_add_u64 v[2:3], v[68:69], 1, s[0:1]
	v_lshl_add_u64 v[102:103], v[2:3], 0, v[84:85]
	v_lshl_add_u64 v[2:3], v[70:71], 1, s[0:1]
	v_lshl_add_u64 v[100:101], v[2:3], 0, v[86:87]
	s_cmp_gt_i32 s41, 7
	s_mov_b64 s[0:1], -1
	s_mul_i32 s10, s39, 0x140
	v_lshl_add_u64 v[92:93], v[0:1], 0, s[12:13]
	v_lshl_add_u64 v[94:95], v[104:105], 0, s[12:13]
	v_lshl_add_u64 v[96:97], v[102:103], 0, s[12:13]
	v_lshl_add_u64 v[98:99], v[100:101], 0, s[12:13]
	s_cbranch_scc0 .LBB0_553
	s_mul_hi_u32 s1, s39, 0x140
	s_add_u32 s0, s30, s10
	s_addc_u32 s1, s31, s1
	v_lshl_add_u64 v[0:1], s[0:1], 0, v[64:65]
	v_lshl_add_u64 v[2:3], v[66:67], 1, s[0:1]
	v_lshl_add_u64 v[4:5], v[68:69], 1, s[0:1]
	v_lshl_add_u64 v[6:7], v[70:71], 1, s[0:1]
	v_readfirstlane_b32 s0, v124
	v_lshl_add_u64 v[0:1], v[0:1], 0, v[84:85]
	s_mov_b32 m0, s0
	v_readfirstlane_b32 s0, v125
	global_load_lds_dwordx4 v[0:1], off
	s_mov_b32 m0, s0
	v_readfirstlane_b32 s0, v126
	v_lshl_add_u64 v[2:3], v[2:3], 0, v[86:87]
	global_load_lds_dwordx4 v[104:105], off
	s_mov_b32 m0, s0
	v_readfirstlane_b32 s0, v127
	global_load_lds_dwordx4 v[2:3], off
	s_mov_b32 m0, s0
	v_readfirstlane_b32 s0, v128
	v_lshl_add_u64 v[4:5], v[4:5], 0, v[84:85]
	global_load_lds_dwordx4 v[102:103], off
	s_mov_b32 m0, s0
	v_readfirstlane_b32 s0, v129
	global_load_lds_dwordx4 v[4:5], off
	s_mov_b32 m0, s0
	v_readfirstlane_b32 s0, v130
	v_lshl_add_u64 v[6:7], v[6:7], 0, v[86:87]
	global_load_lds_dwordx4 v[100:101], off
	s_mov_b32 m0, s0
	v_lshl_add_u64 v[106:107], v[0:1], 0, s[12:13]
	global_load_lds_dwordx4 v[6:7], off
	v_mov_b32_e32 v0, 0
	v_lshl_add_u64 v[108:109], v[2:3], 0, s[12:13]
	v_lshl_add_u64 v[110:111], v[4:5], 0, s[12:13]
	v_lshl_add_u64 v[112:113], v[6:7], 0, s[12:13]
	s_mov_b32 s43, 0
	s_mov_b64 s[0:1], 0
	s_mov_b64 s[2:3], -1
	v_mov_b32_e32 v1, v0
	v_mov_b32_e32 v2, v0
	v_mov_b32_e32 v3, v0
	v_mov_b32_e32 v4, v0
	v_mov_b32_e32 v5, v0
	v_mov_b32_e32 v6, v0
	v_mov_b32_e32 v7, v0
	v_mov_b32_e32 v8, v0
	v_mov_b32_e32 v9, v0
	v_mov_b32_e32 v10, v0
	v_mov_b32_e32 v11, v0
	v_mov_b32_e32 v12, v0
	v_mov_b32_e32 v13, v0
	v_mov_b32_e32 v14, v0
	v_mov_b32_e32 v15, v0
	v_mov_b32_e32 v16, v0
	v_mov_b32_e32 v17, v0
	v_mov_b32_e32 v18, v0
	v_mov_b32_e32 v19, v0
	v_mov_b32_e32 v20, v0
	v_mov_b32_e32 v21, v0
	v_mov_b32_e32 v22, v0
	v_mov_b32_e32 v23, v0
	v_mov_b32_e32 v24, v0
	v_mov_b32_e32 v25, v0
	v_mov_b32_e32 v26, v0
	v_mov_b32_e32 v27, v0
	v_mov_b32_e32 v28, v0
	v_mov_b32_e32 v29, v0
	v_mov_b32_e32 v30, v0
	v_mov_b32_e32 v31, v0
	v_mov_b32_e32 v32, v0
	v_mov_b32_e32 v33, v0
	v_mov_b32_e32 v34, v0
	v_mov_b32_e32 v35, v0
	v_mov_b32_e32 v36, v0
	v_mov_b32_e32 v37, v0
	v_mov_b32_e32 v38, v0
	v_mov_b32_e32 v39, v0
	v_mov_b32_e32 v40, v0
	v_mov_b32_e32 v41, v0
	v_mov_b32_e32 v42, v0
	v_mov_b32_e32 v43, v0
	v_mov_b32_e32 v44, v0
	v_mov_b32_e32 v45, v0
	v_mov_b32_e32 v46, v0
	v_mov_b32_e32 v47, v0
	v_mov_b32_e32 v48, v0
	v_mov_b32_e32 v49, v0
	v_mov_b32_e32 v50, v0
	v_mov_b32_e32 v51, v0
	v_mov_b32_e32 v52, v0
	v_mov_b32_e32 v53, v0
	v_mov_b32_e32 v54, v0
	v_mov_b32_e32 v55, v0
	v_mov_b32_e32 v56, v0
	v_mov_b32_e32 v57, v0
	v_mov_b32_e32 v58, v0
	v_mov_b32_e32 v59, v0
	v_mov_b32_e32 v60, v0
	v_mov_b32_e32 v61, v0
	v_mov_b32_e32 v62, v0
	v_mov_b32_e32 v63, v0
	s_waitcnt vmcnt(0) lgkmcnt(0)
	s_barrier
	s_branch .LBB0_546

; template <bool SW>
; __device__ __forceinline__ void gemm_mainloop(const bf16_t* __restrict__ A, int lda, const bf16_t* __restrict__ Bt, int ldb, int K,
;                                               f32x16 (&acc)[2][2], char* lds, int kstart) {
;     ...
;   for (int i = 0; i < 4; ++i) {
;     const int row = lrow + 8 * i; const int ch = (lane & 7) ^ ((row >> 1) & 7);
;     ap[i] = A + (size_t)row * lda + ch * 8; bp[i] = Bt + (size_t)row * ldb + ch * 8;
;   }
;   char* ldst = lds + (wid * 32) * 128 + lane * 16;
; #pragma unroll
;   for (int i = 0; i < 4; ++i) { glds16(ap[i] + kstart * 64, ldst + i * 1024); glds16(bp[i] + kstart * 64, ldst + 16384 + i * 1024); }
;   asm volatile("s_waitcnt vmcnt(0)" ::: "memory");
;   __syncthreads();
; __device__ __forceinline__ void zero_acc(f32x16 (&acc)[2][2]) {
; #pragma unroll
;   for (int i = 0; i < 2; ++i)
; #pragma unroll
;     for (int j = 0; j < 2; ++j)
; #pragma unroll
;       for (int r = 0; r < 16; ++r) acc[i][j][r] = 0.f;
.LBB0_553:
	s_and_b64 vcc, exec, s[0:1]
	s_cbranch_vccz .LBB0_559
	s_mul_hi_i32 s1, s39, 0x140
	s_add_u32 s0, s30, s10
	s_addc_u32 s1, s31, s1
	v_lshl_add_u64 v[0:1], s[0:1], 0, v[64:65]
	v_mov_b32_e32 v85, v65
	v_lshl_add_u64 v[2:3], v[66:67], 1, s[0:1]
	v_lshl_add_u64 v[4:5], v[68:69], 1, s[0:1]
	v_lshl_add_u64 v[6:7], v[70:71], 1, s[0:1]
	v_readfirstlane_b32 s0, v124
	v_lshl_add_u64 v[0:1], v[0:1], 0, v[84:85]
	s_mov_b32 m0, s0
	v_readfirstlane_b32 s0, v125
	v_mov_b32_e32 v87, v65
	global_load_lds_dwordx4 v[0:1], off
	s_mov_b32 m0, s0
	v_readfirstlane_b32 s0, v126
	v_lshl_add_u64 v[2:3], v[2:3], 0, v[86:87]
	global_load_lds_dwordx4 v[104:105], off
	s_mov_b32 m0, s0
	v_readfirstlane_b32 s0, v127
	global_load_lds_dwordx4 v[2:3], off
	s_mov_b32 m0, s0
	v_readfirstlane_b32 s0, v128
	v_lshl_add_u64 v[4:5], v[4:5], 0, v[84:85]
	global_load_lds_dwordx4 v[102:103], off
	s_mov_b32 m0, s0
	v_readfirstlane_b32 s0, v129
	global_load_lds_dwordx4 v[4:5], off
	s_mov_b32 m0, s0
	v_readfirstlane_b32 s0, v130
	v_lshl_add_u64 v[6:7], v[6:7], 0, v[86:87]
	global_load_lds_dwordx4 v[100:101], off
	s_mov_b32 m0, s0
	v_lshl_add_u64 v[100:101], v[0:1], 0, s[12:13]
	global_load_lds_dwordx4 v[6:7], off
	v_mov_b32_e32 v0, 0
	v_lshl_add_u64 v[102:103], v[2:3], 0, s[12:13]
	v_lshl_add_u64 v[104:105], v[4:5], 0, s[12:13]
	v_lshl_add_u64 v[106:107], v[6:7], 0, s[12:13]
	s_mov_b32 s10, 0
	s_mov_b64 s[0:1], 0
	s_mov_b64 s[2:3], -1
	v_mov_b32_e32 v1, v0
	v_mov_b32_e32 v2, v0
	v_mov_b32_e32 v3, v0
	v_mov_b32_e32 v4, v0
	v_mov_b32_e32 v5, v0
	v_mov_b32_e32 v6, v0
	v_mov_b32_e32 v7, v0
	v_mov_b32_e32 v8, v0
	v_mov_b32_e32 v9, v0
	v_mov_b32_e32 v10, v0
	v_mov_b32_e32 v11, v0
	v_mov_b32_e32 v12, v0
	v_mov_b32_e32 v13, v0
	v_mov_b32_e32 v14, v0
	v_mov_b32_e32 v15, v0
	v_mov_b32_e32 v16, v0
	v_mov_b32_e32 v17, v0
	v_mov_b32_e32 v18, v0
	v_mov_b32_e32 v19, v0
	v_mov_b32_e32 v20, v0
	v_mov_b32_e32 v21, v0
	v_mov_b32_e32 v22, v0
	v_mov_b32_e32 v23, v0
	v_mov_b32_e32 v24, v0
	v_mov_b32_e32 v25, v0
	v_mov_b32_e32 v26, v0
	v_mov_b32_e32 v27, v0
	v_mov_b32_e32 v28, v0
	v_mov_b32_e32 v29, v0
	v_mov_b32_e32 v30, v0
	v_mov_b32_e32 v31, v0
	v_mov_b32_e32 v32, v0
	v_mov_b32_e32 v33, v0
	v_mov_b32_e32 v34, v0
	v_mov_b32_e32 v35, v0
	v_mov_b32_e32 v36, v0
	v_mov_b32_e32 v37, v0
	v_mov_b32_e32 v38, v0
	v_mov_b32_e32 v39, v0
	v_mov_b32_e32 v40, v0
	v_mov_b32_e32 v41, v0
	v_mov_b32_e32 v42, v0
	v_mov_b32_e32 v43, v0
	v_mov_b32_e32 v44, v0
	v_mov_b32_e32 v45, v0
	v_mov_b32_e32 v46, v0
	v_mov_b32_e32 v47, v0
	v_mov_b32_e32 v48, v0
	v_mov_b32_e32 v49, v0
	v_mov_b32_e32 v50, v0
	v_mov_b32_e32 v51, v0
	v_mov_b32_e32 v52, v0
	v_mov_b32_e32 v53, v0
	v_mov_b32_e32 v54, v0
	v_mov_b32_e32 v55, v0
	v_mov_b32_e32 v56, v0
	v_mov_b32_e32 v57, v0
	v_mov_b32_e32 v58, v0
	v_mov_b32_e32 v59, v0
	v_mov_b32_e32 v60, v0
	v_mov_b32_e32 v61, v0
	v_mov_b32_e32 v62, v0
	v_mov_b32_e32 v63, v0
	s_waitcnt vmcnt(0) lgkmcnt(0)
	s_barrier
	s_branch .LBB0_556

; template <bool SW>
; __device__ __forceinline__ void gemm_mainloop(const bf16_t* __restrict__ A, int lda, const bf16_t* __restrict__ Bt, int ldb, int K,
;                                               f32x16 (&acc)[2][2], char* lds, int kstart) {
;     ...
;   for (int i = 0; i < 4; ++i) {
;     const int row = lrow + 8 * i; const int ch = (lane & 7) ^ ((row >> 1) & 7);
;     ap[i] = A + (size_t)row * lda + ch * 8; bp[i] = Bt + (size_t)row * ldb + ch * 8;
;   }
;   char* ldst = lds + (wid * 32) * 128 + lane * 16;
; #pragma unroll
;   for (int i = 0; i < 4; ++i) { glds16(ap[i] + kstart * 64, ldst + i * 1024); glds16(bp[i] + kstart * 64, ldst + 16384 + i * 1024); }
;   asm volatile("s_waitcnt vmcnt(0)" ::: "memory");
;   __syncthreads();
; __device__ __forceinline__ void zero_acc(f32x16 (&acc)[2][2]) {
; #pragma unroll
;   for (int i = 0; i < 2; ++i)
; #pragma unroll
;     for (int j = 0; j < 2; ++j)
; #pragma unroll
;       for (int r = 0; r < 16; ++r) acc[i][j][r] = 0.f;
.LBB0_561:
	s_mul_i32 s0, s38, 0x240
	s_mul_hi_i32 s1, s38, 0x240
	s_add_u32 s0, s22, s0
	s_addc_u32 s1, s23, s1
	s_mul_i32 s2, s39, 0x240
	s_mul_hi_i32 s3, s39, 0x240
	s_add_u32 s2, s78, s2
	v_mov_b32_e32 v77, v65
	s_addc_u32 s3, s79, s3
	v_lshl_add_u64 v[0:1], s[0:1], 0, v[76:77]
	v_mov_b32_e32 v85, v65
	v_lshl_add_u64 v[92:93], v[0:1], 0, v[84:85]
	v_lshl_add_u64 v[0:1], s[2:3], 0, v[76:77]
	v_lshl_add_u64 v[94:95], v[0:1], 0, v[84:85]
	v_lshl_add_u64 v[0:1], s[0:1], 0, v[78:79]
	v_mov_b32_e32 v87, v65
	v_lshl_add_u64 v[96:97], v[0:1], 0, v[86:87]
	v_lshl_add_u64 v[0:1], s[2:3], 0, v[78:79]
	v_lshl_add_u64 v[98:99], v[0:1], 0, v[86:87]
	v_lshl_add_u64 v[0:1], s[0:1], 0, v[80:81]
	s_add_i32 s43, s41, s42
	v_lshl_add_u64 v[100:101], v[0:1], 0, v[84:85]
	v_lshl_add_u64 v[0:1], s[2:3], 0, v[80:81]
	v_lshl_add_u64 v[102:103], v[0:1], 0, v[84:85]
	v_lshl_add_u64 v[0:1], s[0:1], 0, v[82:83]
	s_lshl_b32 s0, s43, 8
	v_lshl_add_u64 v[104:105], v[0:1], 0, v[86:87]
	v_lshl_add_u64 v[0:1], s[2:3], 0, v[82:83]
	s_and_b32 s10, s0, 0x100
	v_readfirstlane_b32 s0, v114
	v_lshl_add_u64 v[106:107], v[0:1], 0, v[86:87]
	v_lshl_add_u64 v[0:1], v[92:93], 0, s[10:11]
	s_mov_b32 m0, s0
	v_readfirstlane_b32 s0, v124
	global_load_lds_dwordx4 v[0:1], off
	v_lshl_add_u64 v[0:1], v[94:95], 0, s[10:11]
	s_mov_b32 m0, s0
	v_readfirstlane_b32 s0, v125
	global_load_lds_dwordx4 v[0:1], off
	v_lshl_add_u64 v[0:1], v[96:97], 0, s[10:11]
	s_mov_b32 m0, s0
	v_readfirstlane_b32 s0, v126
	global_load_lds_dwordx4 v[0:1], off
	v_lshl_add_u64 v[0:1], v[98:99], 0, s[10:11]
	s_mov_b32 m0, s0
	v_readfirstlane_b32 s0, v127
	global_load_lds_dwordx4 v[0:1], off
	v_lshl_add_u64 v[0:1], v[100:101], 0, s[10:11]
	s_mov_b32 m0, s0
	v_readfirstlane_b32 s0, v128
	global_load_lds_dwordx4 v[0:1], off
	v_lshl_add_u64 v[0:1], v[102:103], 0, s[10:11]
	s_mov_b32 m0, s0
	v_readfirstlane_b32 s0, v129
	global_load_lds_dwordx4 v[0:1], off
	v_lshl_add_u64 v[0:1], v[104:105], 0, s[10:11]
	s_mov_b32 m0, s0
	v_readfirstlane_b32 s0, v130
	global_load_lds_dwordx4 v[0:1], off
	v_lshl_add_u64 v[0:1], v[106:107], 0, s[10:11]
	s_mov_b32 m0, s0
	s_lshl_b32 s0, s43, 7
	global_load_lds_dwordx4 v[0:1], off
	v_mov_b32_e32 v0, 0
	s_or_b32 s2, s0, 64
	s_mov_b32 s43, 0
	s_mov_b32 s3, 0
	v_mov_b32_e32 v1, v0
	v_mov_b32_e32 v2, v0
	v_mov_b32_e32 v3, v0
	v_mov_b32_e32 v4, v0
	v_mov_b32_e32 v5, v0
	v_mov_b32_e32 v6, v0
	v_mov_b32_e32 v7, v0
	v_mov_b32_e32 v8, v0
	v_mov_b32_e32 v9, v0
	v_mov_b32_e32 v10, v0
	v_mov_b32_e32 v11, v0
	v_mov_b32_e32 v12, v0
	v_mov_b32_e32 v13, v0
	v_mov_b32_e32 v14, v0
	v_mov_b32_e32 v15, v0
	v_mov_b32_e32 v16, v0
	v_mov_b32_e32 v17, v0
	v_mov_b32_e32 v18, v0
	v_mov_b32_e32 v19, v0
	v_mov_b32_e32 v20, v0
	v_mov_b32_e32 v21, v0
	v_mov_b32_e32 v22, v0
	v_mov_b32_e32 v23, v0
	v_mov_b32_e32 v24, v0
	v_mov_b32_e32 v25, v0
	v_mov_b32_e32 v26, v0
	v_mov_b32_e32 v27, v0
	v_mov_b32_e32 v28, v0
	v_mov_b32_e32 v29, v0
	v_mov_b32_e32 v30, v0
	v_mov_b32_e32 v31, v0
	v_mov_b32_e32 v32, v0
	v_mov_b32_e32 v33, v0
	v_mov_b32_e32 v34, v0
	v_mov_b32_e32 v35, v0
	v_mov_b32_e32 v36, v0
	v_mov_b32_e32 v37, v0
	v_mov_b32_e32 v38, v0
	v_mov_b32_e32 v39, v0
	v_mov_b32_e32 v40, v0
	v_mov_b32_e32 v41, v0
	v_mov_b32_e32 v42, v0
	v_mov_b32_e32 v43, v0
	v_mov_b32_e32 v44, v0
	v_mov_b32_e32 v45, v0
	v_mov_b32_e32 v46, v0
	v_mov_b32_e32 v47, v0
	v_mov_b32_e32 v48, v0
	v_mov_b32_e32 v49, v0
	v_mov_b32_e32 v50, v0
	v_mov_b32_e32 v51, v0
	v_mov_b32_e32 v52, v0
	v_mov_b32_e32 v53, v0
	v_mov_b32_e32 v54, v0
	v_mov_b32_e32 v55, v0
	v_mov_b32_e32 v56, v0
	v_mov_b32_e32 v57, v0
	v_mov_b32_e32 v58, v0
	v_mov_b32_e32 v59, v0
	v_mov_b32_e32 v60, v0
	v_mov_b32_e32 v61, v0
	v_mov_b32_e32 v62, v0
	v_mov_b32_e32 v63, v0
	s_waitcnt vmcnt(0) lgkmcnt(0)
	s_barrier
	s_branch .LBB0_563

; template <bool SW>
; __device__ __forceinline__ void gemm_mainloop(const bf16_t* __restrict__ A, int lda, const bf16_t* __restrict__ Bt, int ldb, int K,
;                                               f32x16 (&acc)[2][2], char* lds, int kstart) {
;     ...
;   for (int i = 0; i < 4; ++i) {
;     const int row = lrow + 8 * i; const int ch = (lane & 7) ^ ((row >> 1) & 7);
;     ap[i] = A + (size_t)row * lda + ch * 8; bp[i] = Bt + (size_t)row * ldb + ch * 8;
;   }
;   char* ldst = lds + (wid * 32) * 128 + lane * 16;
; #pragma unroll
;   for (int i = 0; i < 4; ++i) { glds16(ap[i] + kstart * 64, ldst + i * 1024); glds16(bp[i] + kstart * 64, ldst + 16384 + i * 1024); }
;   asm volatile("s_waitcnt vmcnt(0)" ::: "memory");
;   __syncthreads();
; __device__ __forceinline__ bool tile_at(int nMt, int nNt, int it, int& mt, int& nt) {
;   const int x = blockIdx.x & 7, lb = blockIdx.x >> 3, nloc = gridDim.x >> 3;
;   const int mb = (x * nMt) >> 3, mc = (((x + 1) * nMt) >> 3) - mb;
;   const int idx = lb + it * nloc;
;   if (idx >= mc * nNt) return false;
;   const int g = idx / (8 * nNt); const int rem = idx - g * 8 * nNt;
;   const int left = mc - g * 8; const int gsz = left < 8 ? left : 8;
;   mt = mb + g * 8 + rem % gsz; nt = rem / gsz;
;   return true;
.LBB0_788:
	s_lshr_b32 s1, s0, 3
	s_and_b32 s1, s1, 0xffffff8
	s_sub_i32 s3, s16, s1
	s_min_i32 s3, s3, 8
	s_abs_i32 s10, s3
	v_cvt_f32_u32_e32 v0, s10
	s_sub_i32 s40, 0, s10
	s_lshl_b32 s38, s1, 3
	s_sub_i32 s0, s0, s38
	v_rcp_iflag_f32_e32 v0, v0
	s_abs_i32 s39, s0
	s_xor_b32 s38, s0, s3
	s_add_i32 s1, s1, s13
	v_mul_f32_e32 v0, 0x4f7ffffe, v0
	v_cvt_u32_f32_e32 v0, v0
	s_ashr_i32 s38, s38, 31
	v_mov_b32_e32 v77, v65
	v_mov_b32_e32 v79, v65
	v_readfirstlane_b32 s41, v0
	s_mul_i32 s40, s40, s41
	s_mul_hi_u32 s40, s41, s40
	s_add_i32 s41, s41, s40
	s_mul_hi_u32 s40, s39, s41
	s_mul_i32 s41, s40, s10
	s_sub_i32 s39, s39, s41
	s_add_i32 s42, s40, 1
	s_sub_i32 s41, s39, s10
	s_cmp_ge_u32 s39, s10
	s_cselect_b32 s40, s42, s40
	s_cselect_b32 s39, s41, s39
	s_add_i32 s41, s40, 1
	s_cmp_ge_u32 s39, s10
	s_cselect_b32 s10, s41, s40
	s_xor_b32 s10, s10, s38
	s_sub_i32 s10, s10, s38
	s_mul_i32 s3, s10, s3
	s_sub_i32 s0, s0, s3
	s_add_i32 s45, s1, s0
	s_lshl_b32 s3, s45, 7
	s_mul_i32 s0, s45, 0x22000
	s_mul_hi_i32 s1, s3, 0x440
	s_lshl_b32 s44, s10, 7
	s_lshl_b64 s[38:39], s[0:1], 1
	s_add_u32 s0, s18, s38
	s_mul_i32 s40, s10, 0x22000
	s_mul_hi_i32 s41, s44, 0x440
	s_addc_u32 s1, s19, s39
	s_lshl_b64 s[40:41], s[40:41], 1
	s_add_u32 s42, s72, s40
	s_addc_u32 s43, s73, s41
	v_lshl_add_u64 v[0:1], s[0:1], 0, v[64:65]
	v_lshl_add_u64 v[84:85], v[0:1], 0, v[76:77]
	v_lshl_add_u64 v[0:1], s[42:43], 0, v[64:65]
	v_lshl_add_u64 v[86:87], v[0:1], 0, v[76:77]
	v_lshl_add_u64 v[0:1], s[0:1], 0, v[70:71]
	v_lshl_add_u64 v[88:89], v[0:1], 0, v[78:79]
	v_lshl_add_u64 v[0:1], s[42:43], 0, v[70:71]
	v_lshl_add_u64 v[90:91], v[0:1], 0, v[78:79]
	v_lshl_add_u64 v[0:1], s[0:1], 0, v[72:73]
	s_add_i32 s10, s10, s45
	v_lshl_add_u64 v[92:93], v[0:1], 0, v[76:77]
	v_lshl_add_u64 v[0:1], s[42:43], 0, v[72:73]
	v_lshl_add_u64 v[94:95], v[0:1], 0, v[76:77]
	v_lshl_add_u64 v[0:1], s[0:1], 0, v[74:75]
	s_lshl_b32 s0, s10, 7
	v_lshl_add_u64 v[96:97], v[0:1], 0, v[78:79]
	v_lshl_add_u64 v[0:1], s[42:43], 0, v[74:75]
	s_and_b32 s43, s0, 0x380
	s_lshl_b32 s10, s43, 1
	v_readfirstlane_b32 s1, v102
	v_lshl_add_u64 v[98:99], v[0:1], 0, v[78:79]
	v_lshl_add_u64 v[0:1], v[84:85], 0, s[10:11]
	s_mov_b32 m0, s1
	v_readfirstlane_b32 s1, v111
	global_load_lds_dwordx4 v[0:1], off
	v_lshl_add_u64 v[0:1], v[86:87], 0, s[10:11]
	s_mov_b32 m0, s1
	v_readfirstlane_b32 s1, v112
	global_load_lds_dwordx4 v[0:1], off
	v_lshl_add_u64 v[0:1], v[88:89], 0, s[10:11]
	s_mov_b32 m0, s1
	v_readfirstlane_b32 s1, v113
	global_load_lds_dwordx4 v[0:1], off
	v_lshl_add_u64 v[0:1], v[90:91], 0, s[10:11]
	s_mov_b32 m0, s1
	v_readfirstlane_b32 s1, v114
	global_load_lds_dwordx4 v[0:1], off
	v_lshl_add_u64 v[0:1], v[92:93], 0, s[10:11]
	s_mov_b32 m0, s1
	v_readfirstlane_b32 s1, v115
	global_load_lds_dwordx4 v[0:1], off
	v_lshl_add_u64 v[0:1], v[94:95], 0, s[10:11]
	s_mov_b32 m0, s1
	v_readfirstlane_b32 s1, v116
	global_load_lds_dwordx4 v[0:1], off
	v_lshl_add_u64 v[0:1], v[96:97], 0, s[10:11]
	s_mov_b32 m0, s1
	v_readfirstlane_b32 s1, v117
	global_load_lds_dwordx4 v[0:1], off
	v_lshl_add_u64 v[0:1], v[98:99], 0, s[10:11]
	s_mov_b32 m0, s1
	s_or_b32 s42, s0, 64
	global_load_lds_dwordx4 v[0:1], off
	v_mov_b32_e32 v0, 0
	s_mov_b32 s45, s42
	s_mov_b32 s47, 0
	s_mov_b32 s46, 0
	v_mov_b32_e32 v1, v0
	v_mov_b32_e32 v2, v0
	v_mov_b32_e32 v3, v0
	v_mov_b32_e32 v4, v0
	v_mov_b32_e32 v5, v0
	v_mov_b32_e32 v6, v0
	v_mov_b32_e32 v7, v0
	v_mov_b32_e32 v8, v0
	v_mov_b32_e32 v9, v0
	v_mov_b32_e32 v10, v0
	v_mov_b32_e32 v11, v0
	v_mov_b32_e32 v12, v0
	v_mov_b32_e32 v13, v0
	v_mov_b32_e32 v14, v0
	v_mov_b32_e32 v15, v0
	v_mov_b32_e32 v16, v0
	v_mov_b32_e32 v17, v0
	v_mov_b32_e32 v18, v0
	v_mov_b32_e32 v19, v0
	v_mov_b32_e32 v20, v0
	v_mov_b32_e32 v21, v0
	v_mov_b32_e32 v22, v0
	v_mov_b32_e32 v23, v0
	v_mov_b32_e32 v24, v0
	v_mov_b32_e32 v25, v0
	v_mov_b32_e32 v26, v0
	v_mov_b32_e32 v27, v0
	v_mov_b32_e32 v28, v0
	v_mov_b32_e32 v29, v0
	v_mov_b32_e32 v30, v0
	v_mov_b32_e32 v31, v0
	v_mov_b32_e32 v32, v0
	v_mov_b32_e32 v33, v0
	v_mov_b32_e32 v34, v0
	v_mov_b32_e32 v35, v0
	v_mov_b32_e32 v36, v0
	v_mov_b32_e32 v37, v0
	v_mov_b32_e32 v38, v0
	v_mov_b32_e32 v39, v0
	v_mov_b32_e32 v40, v0
	v_mov_b32_e32 v41, v0
	v_mov_b32_e32 v42, v0
	v_mov_b32_e32 v43, v0
	v_mov_b32_e32 v44, v0
	v_mov_b32_e32 v45, v0
	v_mov_b32_e32 v46, v0
	v_mov_b32_e32 v47, v0
	v_mov_b32_e32 v48, v0
	v_mov_b32_e32 v49, v0
	v_mov_b32_e32 v50, v0
	v_mov_b32_e32 v51, v0
	v_mov_b32_e32 v52, v0
	v_mov_b32_e32 v53, v0
	v_mov_b32_e32 v54, v0
	v_mov_b32_e32 v55, v0
	v_mov_b32_e32 v56, v0
	v_mov_b32_e32 v57, v0
	v_mov_b32_e32 v58, v0
	v_mov_b32_e32 v59, v0
	v_mov_b32_e32 v60, v0
	v_mov_b32_e32 v61, v0
	v_mov_b32_e32 v62, v0
	v_mov_b32_e32 v63, v0
	s_waitcnt vmcnt(0) lgkmcnt(0)
	s_barrier
	s_branch .LBB0_790

; __device__ __forceinline__ unsigned pk2(float lo, float hi) { f32v2_t v = {lo, hi}; bf16v2_t r = __builtin_convertvector(v, bf16v2_t); return __builtin_bit_cast(unsigned, r); }
; __device__ __forceinline__ float bflo(unsigned w) { return __uint_as_float(w << 16); }
; __device__ __forceinline__ float bfhi(unsigned w) { return __uint_as_float(w & 0xffff0000u); }
; __device__ void phase_merge(const Params& p, char* lds) {
;     ...
; #pragma unroll
;       for (int i = 0; i < 2; ++i)
; #pragma unroll
;         for (int j = 0; j < 2; ++j) {
;           const int tok = m0 + wr * 64 + i * 32 + l31; const int cb = n0 + wc * 64 + j * 32;
;           const bf16_t* gp = gates + (size_t)tok * 2048 + cb + 4 * hh;
;           bf16_t* op = mg + (size_t)tok * LDH + cb + 4 * hh;
; #pragma unroll
;           for (int g = 0; g < 4; ++g) {
;             const u32x2 gv = *(const u32x2*)(gp + 8 * g);
;             u32x2 w;
;             w.x = pk2(acc[i][j][4 * g] * bflo(gv.x), acc[i][j][4 * g + 1] * bfhi(gv.x));
;             w.y = pk2(acc[i][j][4 * g + 2] * bflo(gv.y), acc[i][j][4 * g + 3] * bfhi(gv.y));
;             *(u32x2*)(op + 8 * g) = w;
;           }
.LBB0_794:
	v_and_b32_e32 v123, 63, v181
	v_lshrrev_b32_e32 v122, 6, v181
	v_and_b32_e32 v118, 31, v123
	v_lshrrev_b32_e32 v119, 5, v123
	v_mul_u32_u24_e32 v118, 0x110, v118
	v_lshlrev_b32_e32 v119, 4, v119
	v_mul_u32_u24_e32 v120, 0x2200, v122
	v_add3_u32 v118, v118, v119, v120
	v_add_u32_e32 v118, 0x8000, v118
	v_add_u32_e32 v119, 0x8000, v120
	v_lshrrev_b32_e32 v120, 3, v123
	v_and_b32_e32 v121, 7, v123
	v_mul_u32_u24_e32 v123, 0x110, v120
	v_add_u32_e32 v119, v119, v123
	v_lshl_add_u32 v119, v121, 5, v119
	v_readlane_b32 vcc_lo, v248, 4
	v_readlane_b32 vcc_hi, v248, 5
	s_lshl_b32 s0, s3, 12
	s_lshl_b32 s1, s44, 1
	s_add_i32 s0, s0, s1
	s_mul_i32 s10, s3, 0x880
	s_add_i32 s1, s1, s10
	s_add_i32 s1, s1, 0x1699e000
	v_lshrrev_b32_e32 v124, 1, v122
	v_mul_u32_u24_e32 v124, 0x40000, v124
	v_mul_u32_u24_e32 v126, 0x1000, v120
	v_add_u32_e32 v124, v124, v126
	v_and_b32_e32 v126, 1, v122
	v_mul_u32_u24_e32 v126, 0x80, v126
	v_lshl_add_u32 v126, v121, 4, v126
	v_add3_u32 v124, v124, v126, s0
	v_lshrrev_b32_e32 v125, 1, v122
	v_mul_u32_u24_e32 v125, 0x22000, v125
	v_mul_u32_u24_e32 v126, 0x880, v120
	v_add_u32_e32 v125, v125, v126
	v_and_b32_e32 v126, 1, v122
	v_mul_u32_u24_e32 v126, 0x80, v126
	v_lshl_add_u32 v126, v121, 4, v126
	v_add3_u32 v125, v125, v126, s1
	ds_write_b128 v118, v[48:51] offset:0
	ds_write_b128 v118, v[52:55] offset:32
	ds_write_b128 v118, v[56:59] offset:64
	ds_write_b128 v118, v[60:63] offset:96
	ds_write_b128 v118, v[32:35] offset:128
	ds_write_b128 v118, v[36:39] offset:160
	ds_write_b128 v118, v[40:43] offset:192
	ds_write_b128 v118, v[44:47] offset:224
	s_waitcnt lgkmcnt(0)
	global_load_dwordx4 v[84:87], v124, vcc offset:0
	v_add_u32_e32 v124, 0x8000, v124
	global_load_dwordx4 v[88:91], v124, vcc offset:0
	v_add_u32_e32 v124, 0x8000, v124
	global_load_dwordx4 v[92:95], v124, vcc offset:0
	v_add_u32_e32 v124, 0x8000, v124
	global_load_dwordx4 v[96:99], v124, vcc offset:0
	v_add_u32_e32 v124, 0x8000, v124
	ds_read_b128 v[32:35], v119 offset:0
	ds_read_b128 v[36:39], v119 offset:16
	ds_read_b128 v[40:43], v119 offset:2176
	ds_read_b128 v[44:47], v119 offset:2192
	s_waitcnt vmcnt(3) lgkmcnt(2)
	v_lshlrev_b32_e32 v127, 16, v84
	v_mul_f32_e32 v32, v32, v127
	v_and_b32_e32 v127, 0xffff0000, v84
	v_mul_f32_e32 v33, v33, v127
	v_lshlrev_b32_e32 v127, 16, v85
	v_mul_f32_e32 v34, v34, v127
	v_and_b32_e32 v127, 0xffff0000, v85
	v_mul_f32_e32 v35, v35, v127
	v_lshlrev_b32_e32 v127, 16, v86
	v_mul_f32_e32 v36, v36, v127
	v_and_b32_e32 v127, 0xffff0000, v86
	v_mul_f32_e32 v37, v37, v127
	v_lshlrev_b32_e32 v127, 16, v87
	v_mul_f32_e32 v38, v38, v127
	v_and_b32_e32 v127, 0xffff0000, v87
	v_mul_f32_e32 v39, v39, v127
	v_cvt_pk_bf16_f32 v32, v32, v33
	v_cvt_pk_bf16_f32 v33, v34, v35
	v_cvt_pk_bf16_f32 v34, v36, v37
	v_cvt_pk_bf16_f32 v35, v38, v39
	global_store_dwordx4 v125, v[32:35], s[96:97]
	v_add_u32_e32 v125, 0x4400, v125
	s_waitcnt vmcnt(3) lgkmcnt(0)
	v_lshlrev_b32_e32 v127, 16, v88
	v_mul_f32_e32 v40, v40, v127
	v_and_b32_e32 v127, 0xffff0000, v88
	v_mul_f32_e32 v41, v41, v127
	v_lshlrev_b32_e32 v127, 16, v89
	v_mul_f32_e32 v42, v42, v127
	v_and_b32_e32 v127, 0xffff0000, v89
	v_mul_f32_e32 v43, v43, v127
	v_lshlrev_b32_e32 v127, 16, v90
	v_mul_f32_e32 v44, v44, v127
	v_and_b32_e32 v127, 0xffff0000, v90
	v_mul_f32_e32 v45, v45, v127
	v_lshlrev_b32_e32 v127, 16, v91
	v_mul_f32_e32 v46, v46, v127
	v_and_b32_e32 v127, 0xffff0000, v91
	v_mul_f32_e32 v47, v47, v127
	v_cvt_pk_bf16_f32 v40, v40, v41
	v_cvt_pk_bf16_f32 v41, v42, v43
	v_cvt_pk_bf16_f32 v42, v44, v45
	v_cvt_pk_bf16_f32 v43, v46, v47
	global_store_dwordx4 v125, v[40:43], s[96:97]
	v_add_u32_e32 v125, 0x4400, v125
	ds_read_b128 v[32:35], v119 offset:4352
	ds_read_b128 v[36:39], v119 offset:4368
	ds_read_b128 v[40:43], v119 offset:6528
	ds_read_b128 v[44:47], v119 offset:6544
	s_waitcnt vmcnt(3) lgkmcnt(2)
	v_lshlrev_b32_e32 v127, 16, v92
	v_mul_f32_e32 v32, v32, v127
	v_and_b32_e32 v127, 0xffff0000, v92
	v_mul_f32_e32 v33, v33, v127
	v_lshlrev_b32_e32 v127, 16, v93
	v_mul_f32_e32 v34, v34, v127
	v_and_b32_e32 v127, 0xffff0000, v93
	v_mul_f32_e32 v35, v35, v127
	v_lshlrev_b32_e32 v127, 16, v94
	v_mul_f32_e32 v36, v36, v127
	v_and_b32_e32 v127, 0xffff0000, v94
	v_mul_f32_e32 v37, v37, v127
	v_lshlrev_b32_e32 v127, 16, v95
	v_mul_f32_e32 v38, v38, v127
	v_and_b32_e32 v127, 0xffff0000, v95
	v_mul_f32_e32 v39, v39, v127
	v_cvt_pk_bf16_f32 v32, v32, v33
	v_cvt_pk_bf16_f32 v33, v34, v35
	v_cvt_pk_bf16_f32 v34, v36, v37
	v_cvt_pk_bf16_f32 v35, v38, v39
	global_store_dwordx4 v125, v[32:35], s[96:97]
	v_add_u32_e32 v125, 0x4400, v125
	s_waitcnt vmcnt(3) lgkmcnt(0)
	v_lshlrev_b32_e32 v127, 16, v96
	v_mul_f32_e32 v40, v40, v127
	v_and_b32_e32 v127, 0xffff0000, v96
	v_mul_f32_e32 v41, v41, v127
	v_lshlrev_b32_e32 v127, 16, v97
	v_mul_f32_e32 v42, v42, v127
	v_and_b32_e32 v127, 0xffff0000, v97
	v_mul_f32_e32 v43, v43, v127
	v_lshlrev_b32_e32 v127, 16, v98
	v_mul_f32_e32 v44, v44, v127
	v_and_b32_e32 v127, 0xffff0000, v98
	v_mul_f32_e32 v45, v45, v127
	v_lshlrev_b32_e32 v127, 16, v99
	v_mul_f32_e32 v46, v46, v127
	v_and_b32_e32 v127, 0xffff0000, v99
	v_mul_f32_e32 v47, v47, v127
	v_cvt_pk_bf16_f32 v40, v40, v41
	v_cvt_pk_bf16_f32 v41, v42, v43
	v_cvt_pk_bf16_f32 v42, v44, v45
	v_cvt_pk_bf16_f32 v43, v46, v47
	global_store_dwordx4 v125, v[40:43], s[96:97]
	v_add_u32_e32 v125, 0x4400, v125
	ds_write_b128 v118, v[16:19] offset:0
	ds_write_b128 v118, v[20:23] offset:32
	ds_write_b128 v118, v[24:27] offset:64
	ds_write_b128 v118, v[28:31] offset:96
	ds_write_b128 v118, v[0:3] offset:128
	ds_write_b128 v118, v[4:7] offset:160
	ds_write_b128 v118, v[8:11] offset:192
	ds_write_b128 v118, v[12:15] offset:224
	s_waitcnt lgkmcnt(0)
; __device__ __forceinline__ unsigned pk2(float lo, float hi) { f32v2_t v = {lo, hi}; bf16v2_t r = __builtin_convertvector(v, bf16v2_t); return __builtin_bit_cast(unsigned, r); }
; __device__ __forceinline__ float bflo(unsigned w) { return __uint_as_float(w << 16); }
; __device__ __forceinline__ float bfhi(unsigned w) { return __uint_as_float(w & 0xffff0000u); }
; __device__ void phase_merge(const Params& p, char* lds) {
;     ...
;           const bf16_t* gp = gates + (size_t)tok * 2048 + cb + 4 * hh;
;           bf16_t* op = mg + (size_t)tok * LDH + cb + 4 * hh;
; #pragma unroll
;           for (int g = 0; g < 4; ++g) {
;             const u32x2 gv = *(const u32x2*)(gp + 8 * g);
;             u32x2 w;
;             w.x = pk2(acc[i][j][4 * g] * bflo(gv.x), acc[i][j][4 * g + 1] * bfhi(gv.x));
;             w.y = pk2(acc[i][j][4 * g + 2] * bflo(gv.y), acc[i][j][4 * g + 3] * bfhi(gv.y));
;             *(u32x2*)(op + 8 * g) = w;
;           }
	global_load_dwordx4 v[84:87], v124, vcc offset:0
	v_add_u32_e32 v124, 0x8000, v124
	global_load_dwordx4 v[88:91], v124, vcc offset:0
	v_add_u32_e32 v124, 0x8000, v124
	global_load_dwordx4 v[92:95], v124, vcc offset:0
	v_add_u32_e32 v124, 0x8000, v124
	global_load_dwordx4 v[96:99], v124, vcc offset:0
	v_add_u32_e32 v124, 0x8000, v124
	ds_read_b128 v[0:3], v119 offset:0
	ds_read_b128 v[4:7], v119 offset:16
	ds_read_b128 v[8:11], v119 offset:2176
	ds_read_b128 v[12:15], v119 offset:2192
	s_waitcnt vmcnt(3) lgkmcnt(2)
	v_lshlrev_b32_e32 v127, 16, v84
	v_mul_f32_e32 v0, v0, v127
	v_and_b32_e32 v127, 0xffff0000, v84
	v_mul_f32_e32 v1, v1, v127
	v_lshlrev_b32_e32 v127, 16, v85
	v_mul_f32_e32 v2, v2, v127
	v_and_b32_e32 v127, 0xffff0000, v85
	v_mul_f32_e32 v3, v3, v127
	v_lshlrev_b32_e32 v127, 16, v86
	v_mul_f32_e32 v4, v4, v127
	v_and_b32_e32 v127, 0xffff0000, v86
	v_mul_f32_e32 v5, v5, v127
	v_lshlrev_b32_e32 v127, 16, v87
	v_mul_f32_e32 v6, v6, v127
	v_and_b32_e32 v127, 0xffff0000, v87
	v_mul_f32_e32 v7, v7, v127
	v_cvt_pk_bf16_f32 v0, v0, v1
	v_cvt_pk_bf16_f32 v1, v2, v3
	v_cvt_pk_bf16_f32 v2, v4, v5
	v_cvt_pk_bf16_f32 v3, v6, v7
	global_store_dwordx4 v125, v[0:3], s[96:97]
	v_add_u32_e32 v125, 0x4400, v125
	s_waitcnt vmcnt(3) lgkmcnt(0)
	v_lshlrev_b32_e32 v127, 16, v88
	v_mul_f32_e32 v8, v8, v127
	v_and_b32_e32 v127, 0xffff0000, v88
	v_mul_f32_e32 v9, v9, v127
	v_lshlrev_b32_e32 v127, 16, v89
	v_mul_f32_e32 v10, v10, v127
	v_and_b32_e32 v127, 0xffff0000, v89
	v_mul_f32_e32 v11, v11, v127
	v_lshlrev_b32_e32 v127, 16, v90
	v_mul_f32_e32 v12, v12, v127
	v_and_b32_e32 v127, 0xffff0000, v90
	v_mul_f32_e32 v13, v13, v127
	v_lshlrev_b32_e32 v127, 16, v91
	v_mul_f32_e32 v14, v14, v127
	v_and_b32_e32 v127, 0xffff0000, v91
	v_mul_f32_e32 v15, v15, v127
	v_cvt_pk_bf16_f32 v8, v8, v9
	v_cvt_pk_bf16_f32 v9, v10, v11
	v_cvt_pk_bf16_f32 v10, v12, v13
	v_cvt_pk_bf16_f32 v11, v14, v15
	global_store_dwordx4 v125, v[8:11], s[96:97]
	v_add_u32_e32 v125, 0x4400, v125
	ds_read_b128 v[0:3], v119 offset:4352
	ds_read_b128 v[4:7], v119 offset:4368
	ds_read_b128 v[8:11], v119 offset:6528
	ds_read_b128 v[12:15], v119 offset:6544
	s_waitcnt vmcnt(3) lgkmcnt(2)
	v_lshlrev_b32_e32 v127, 16, v92
	v_mul_f32_e32 v0, v0, v127
	v_and_b32_e32 v127, 0xffff0000, v92
	v_mul_f32_e32 v1, v1, v127
	v_lshlrev_b32_e32 v127, 16, v93
	v_mul_f32_e32 v2, v2, v127
	v_and_b32_e32 v127, 0xffff0000, v93
	v_mul_f32_e32 v3, v3, v127
	v_lshlrev_b32_e32 v127, 16, v94
	v_mul_f32_e32 v4, v4, v127
	v_and_b32_e32 v127, 0xffff0000, v94
	v_mul_f32_e32 v5, v5, v127
	v_lshlrev_b32_e32 v127, 16, v95
	v_mul_f32_e32 v6, v6, v127
	v_and_b32_e32 v127, 0xffff0000, v95
	v_mul_f32_e32 v7, v7, v127
	v_cvt_pk_bf16_f32 v0, v0, v1
	v_cvt_pk_bf16_f32 v1, v2, v3
	v_cvt_pk_bf16_f32 v2, v4, v5
	v_cvt_pk_bf16_f32 v3, v6, v7
	global_store_dwordx4 v125, v[0:3], s[96:97]
	v_add_u32_e32 v125, 0x4400, v125
	s_waitcnt vmcnt(3) lgkmcnt(0)
; __device__ __forceinline__ unsigned pk2(float lo, float hi) { f32v2_t v = {lo, hi}; bf16v2_t r = __builtin_convertvector(v, bf16v2_t); return __builtin_bit_cast(unsigned, r); }
; __device__ __forceinline__ float bflo(unsigned w) { return __uint_as_float(w << 16); }
; __device__ __forceinline__ float bfhi(unsigned w) { return __uint_as_float(w & 0xffff0000u); }
; template <bool SW>
; __device__ __forceinline__ void gemm_mainloop(const bf16_t* __restrict__ A, int lda, const bf16_t* __restrict__ Bt, int ldb, int K,
;                                               f32x16 (&acc)[2][2], char* lds, int kstart) {
;     ...
;   for (int i = 0; i < 4; ++i) {
;     const int row = lrow + 8 * i; const int ch = (lane & 7) ^ ((row >> 1) & 7);
;     ap[i] = A + (size_t)row * lda + ch * 8; bp[i] = Bt + (size_t)row * ldb + ch * 8;
;   }
;   char* ldst = lds + (wid * 32) * 128 + lane * 16;
; #pragma unroll
;   for (int i = 0; i < 4; ++i) { glds16(ap[i] + kstart * 64, ldst + i * 1024); glds16(bp[i] + kstart * 64, ldst + 16384 + i * 1024); }
;   asm volatile("s_waitcnt vmcnt(0)" ::: "memory");
;   __syncthreads();
; __device__ void phase_merge(const Params& p, char* lds) {
;     ...
;             w.x = pk2(acc[i][j][4 * g] * bflo(gv.x), acc[i][j][4 * g + 1] * bfhi(gv.x));
;             w.y = pk2(acc[i][j][4 * g + 2] * bflo(gv.y), acc[i][j][4 * g + 3] * bfhi(gv.y));
;             *(u32x2*)(op + 8 * g) = w;
	v_lshlrev_b32_e32 v127, 16, v96
	v_mul_f32_e32 v8, v8, v127
	v_and_b32_e32 v127, 0xffff0000, v96
	v_mul_f32_e32 v9, v9, v127
	v_lshlrev_b32_e32 v127, 16, v97
	v_mul_f32_e32 v10, v10, v127
	v_and_b32_e32 v127, 0xffff0000, v97
	v_mul_f32_e32 v11, v11, v127
	v_lshlrev_b32_e32 v127, 16, v98
	v_mul_f32_e32 v12, v12, v127
	v_and_b32_e32 v127, 0xffff0000, v98
	v_mul_f32_e32 v13, v13, v127
	v_lshlrev_b32_e32 v127, 16, v99
	v_mul_f32_e32 v14, v14, v127
	v_and_b32_e32 v127, 0xffff0000, v99
	v_mul_f32_e32 v15, v15, v127
	v_cvt_pk_bf16_f32 v8, v8, v9
	v_cvt_pk_bf16_f32 v9, v10, v11
	v_cvt_pk_bf16_f32 v10, v12, v13
	v_cvt_pk_bf16_f32 v11, v14, v15
	global_store_dwordx4 v125, v[8:11], s[96:97]
	v_add_u32_e32 v125, 0x4400, v125
	v_mov_b32_e32 v77, v65
	v_mov_b32_e32 v79, v65
	s_add_u32 s0, s24, s38
	s_addc_u32 s1, s25, s39
	s_add_u32 s38, s26, s40
	s_addc_u32 s39, s27, s41
	s_lshl_b32 s10, s43, 1
	v_lshl_add_u64 v[0:1], s[0:1], 0, v[64:65]
	v_lshl_add_u64 v[86:87], v[0:1], 0, v[76:77]
	v_lshl_add_u64 v[0:1], s[38:39], 0, v[64:65]
	v_lshl_add_u64 v[88:89], v[0:1], 0, v[76:77]
	v_lshl_add_u64 v[0:1], s[0:1], 0, v[70:71]
	v_lshl_add_u64 v[90:91], v[0:1], 0, v[78:79]
	v_lshl_add_u64 v[0:1], s[38:39], 0, v[70:71]
	v_lshl_add_u64 v[92:93], v[0:1], 0, v[78:79]
	v_lshl_add_u64 v[0:1], s[0:1], 0, v[72:73]
	v_lshl_add_u64 v[94:95], v[0:1], 0, v[76:77]
	v_lshl_add_u64 v[0:1], s[38:39], 0, v[72:73]
	v_lshl_add_u64 v[96:97], v[0:1], 0, v[76:77]
	v_lshl_add_u64 v[0:1], s[0:1], 0, v[74:75]
	v_lshl_add_u64 v[98:99], v[0:1], 0, v[78:79]
	v_lshl_add_u64 v[0:1], s[38:39], 0, v[74:75]
	v_readfirstlane_b32 s0, v102
	v_lshl_add_u64 v[100:101], v[0:1], 0, v[78:79]
	v_lshl_add_u64 v[0:1], v[86:87], 0, s[10:11]
	s_mov_b32 m0, s0
	v_readfirstlane_b32 s0, v111
	global_load_lds_dwordx4 v[0:1], off
	v_lshl_add_u64 v[0:1], v[88:89], 0, s[10:11]
	s_mov_b32 m0, s0
	v_readfirstlane_b32 s0, v112
	global_load_lds_dwordx4 v[0:1], off
	v_lshl_add_u64 v[0:1], v[90:91], 0, s[10:11]
	s_mov_b32 m0, s0
	v_readfirstlane_b32 s0, v113
	global_load_lds_dwordx4 v[0:1], off
	v_lshl_add_u64 v[0:1], v[92:93], 0, s[10:11]
	s_mov_b32 m0, s0
	v_readfirstlane_b32 s0, v114
	global_load_lds_dwordx4 v[0:1], off
	v_lshl_add_u64 v[0:1], v[94:95], 0, s[10:11]
	s_mov_b32 m0, s0
	v_readfirstlane_b32 s0, v115
	global_load_lds_dwordx4 v[0:1], off
	v_lshl_add_u64 v[0:1], v[96:97], 0, s[10:11]
	s_mov_b32 m0, s0
	v_readfirstlane_b32 s0, v116
	global_load_lds_dwordx4 v[0:1], off
	v_lshl_add_u64 v[0:1], v[98:99], 0, s[10:11]
	s_mov_b32 m0, s0
	v_readfirstlane_b32 s0, v117
	global_load_lds_dwordx4 v[0:1], off
	v_lshl_add_u64 v[0:1], v[100:101], 0, s[10:11]
	s_mov_b32 m0, s0
	s_mov_b32 s39, 0
	global_load_lds_dwordx4 v[0:1], off
	v_mov_b32_e32 v0, 0
	s_mov_b32 s38, 0
	v_mov_b32_e32 v1, v0
	v_mov_b32_e32 v2, v0
	v_mov_b32_e32 v3, v0
	v_mov_b32_e32 v4, v0
	v_mov_b32_e32 v5, v0
	v_mov_b32_e32 v6, v0
	v_mov_b32_e32 v7, v0
	v_mov_b32_e32 v8, v0
	v_mov_b32_e32 v9, v0
	v_mov_b32_e32 v10, v0
	v_mov_b32_e32 v11, v0
	v_mov_b32_e32 v12, v0
	v_mov_b32_e32 v13, v0
	v_mov_b32_e32 v14, v0
	v_mov_b32_e32 v15, v0
	v_mov_b32_e32 v16, v0
	v_mov_b32_e32 v17, v0
	v_mov_b32_e32 v18, v0
	v_mov_b32_e32 v19, v0
	v_mov_b32_e32 v20, v0
	v_mov_b32_e32 v21, v0
	v_mov_b32_e32 v22, v0
	v_mov_b32_e32 v23, v0
	v_mov_b32_e32 v24, v0
	v_mov_b32_e32 v25, v0
	v_mov_b32_e32 v26, v0
	v_mov_b32_e32 v27, v0
	v_mov_b32_e32 v28, v0
	v_mov_b32_e32 v29, v0
	v_mov_b32_e32 v30, v0
	v_mov_b32_e32 v31, v0
	v_mov_b32_e32 v32, v0
	v_mov_b32_e32 v33, v0
	v_mov_b32_e32 v34, v0
	v_mov_b32_e32 v35, v0
	v_mov_b32_e32 v36, v0
	v_mov_b32_e32 v37, v0
	v_mov_b32_e32 v38, v0
	v_mov_b32_e32 v39, v0
	v_mov_b32_e32 v40, v0
	v_mov_b32_e32 v41, v0
	v_mov_b32_e32 v42, v0
	v_mov_b32_e32 v43, v0
	v_mov_b32_e32 v44, v0
	v_mov_b32_e32 v45, v0
	v_mov_b32_e32 v46, v0
	v_mov_b32_e32 v47, v0
	v_mov_b32_e32 v48, v0
	v_mov_b32_e32 v49, v0
	v_mov_b32_e32 v50, v0
	v_mov_b32_e32 v51, v0
	v_mov_b32_e32 v52, v0
	v_mov_b32_e32 v53, v0
	v_mov_b32_e32 v54, v0
	v_mov_b32_e32 v55, v0
	v_mov_b32_e32 v56, v0
	v_mov_b32_e32 v57, v0
	v_mov_b32_e32 v58, v0
	v_mov_b32_e32 v59, v0
	v_mov_b32_e32 v60, v0
	v_mov_b32_e32 v61, v0
	v_mov_b32_e32 v62, v0
	v_mov_b32_e32 v63, v0
	s_waitcnt vmcnt(0) lgkmcnt(0)
	s_barrier
	s_branch .LBB0_796

; template <bool SW>
; __device__ __forceinline__ void gemm_mainloop(const bf16_t* __restrict__ A, int lda, const bf16_t* __restrict__ Bt, int ldb, int K,
;                                               f32x16 (&acc)[2][2], char* lds, int kstart) {
;     ...
;   for (int i = 0; i < 4; ++i) {
;     const int row = lrow + 8 * i; const int ch = (lane & 7) ^ ((row >> 1) & 7);
;     ap[i] = A + (size_t)row * lda + ch * 8; bp[i] = Bt + (size_t)row * ldb + ch * 8;
;   }
;   char* ldst = lds + (wid * 32) * 128 + lane * 16;
; #pragma unroll
;   for (int i = 0; i < 4; ++i) { glds16(ap[i] + kstart * 64, ldst + i * 1024); glds16(bp[i] + kstart * 64, ldst + 16384 + i * 1024); }
;   asm volatile("s_waitcnt vmcnt(0)" ::: "memory");
;   __syncthreads();
; __device__ void phase_outproj(const Params& p, char* lds) {
;     ...
;     int mt, nt; if (!tile_at(260, 8, it, mt, nt)) break;
;     const int m0 = mt * 128, n0 = nt * 128;
;     f32x16 acc[2][2]; zero_acc(acc);
;     gemm_mainloop<true>((const bf16_t*)(ws + W_F) + (size_t)m0 * LDH, LDH, (const bf16_t*)(ws + W_WO) + (size_t)n0 * LDH, LDH, 1024, acc, lds, 2 * ((mt + nt) & 7));
.LBB0_870:
	s_lshr_b32 s1, s0, 3
	s_and_b32 s1, s1, 0xffffff8
	s_sub_i32 s3, s33, s1
	s_min_i32 s3, s3, 8
	s_abs_i32 s12, s3
	v_cvt_f32_u32_e32 v0, s12
	s_sub_i32 s40, 0, s12
	s_lshl_b32 s38, s1, 3
	s_sub_i32 s0, s0, s38
	v_rcp_iflag_f32_e32 v0, v0
	s_abs_i32 s39, s0
	s_xor_b32 s38, s0, s3
	s_add_i32 s1, s1, s19
	v_mul_f32_e32 v0, 0x4f7ffffe, v0
	v_cvt_u32_f32_e32 v0, v0
	s_ashr_i32 s38, s38, 31
	v_mov_b32_e32 v67, v65
	v_mov_b32_e32 v71, v65
	v_readfirstlane_b32 s41, v0
	s_mul_i32 s40, s40, s41
	s_mul_hi_u32 s40, s41, s40
	s_add_i32 s41, s41, s40
	s_mul_hi_u32 s40, s39, s41
	s_mul_i32 s41, s40, s12
	s_sub_i32 s39, s39, s41
	s_add_i32 s42, s40, 1
	s_sub_i32 s41, s39, s12
	s_cmp_ge_u32 s39, s12
	s_cselect_b32 s40, s42, s40
	s_cselect_b32 s39, s41, s39
	s_add_i32 s41, s40, 1
	s_cmp_ge_u32 s39, s12
	s_cselect_b32 s12, s41, s40
	s_xor_b32 s12, s12, s38
	s_sub_i32 s12, s12, s38
	s_mul_i32 s3, s12, s3
	s_sub_i32 s0, s0, s3
	s_add_i32 s39, s1, s0
	s_lshl_b32 s3, s39, 7
	s_lshl_b32 s38, s12, 7
	s_mul_i32 s0, s39, 0x44000
	s_mul_hi_i32 s1, s3, 0x880
	s_add_u32 s0, s73, s0
	s_addc_u32 s1, s24, s1
	s_mul_i32 s40, s12, 0x44000
	s_mul_hi_i32 s41, s38, 0x880
	s_add_u32 s40, s25, s40
	s_addc_u32 s41, s16, s41
	v_lshl_add_u64 v[0:1], s[0:1], 0, v[64:65]
	v_lshl_add_u64 v[80:81], v[0:1], 0, v[66:67]
	v_lshl_add_u64 v[0:1], s[40:41], 0, v[64:65]
	v_lshl_add_u64 v[82:83], v[0:1], 0, v[66:67]
	v_lshl_add_u64 v[0:1], s[0:1], 0, v[68:69]
	v_lshl_add_u64 v[84:85], v[0:1], 0, v[70:71]
	v_lshl_add_u64 v[0:1], s[40:41], 0, v[68:69]
	v_lshl_add_u64 v[86:87], v[0:1], 0, v[70:71]
	v_lshl_add_u64 v[0:1], s[0:1], 0, v[72:73]
	s_add_i32 s39, s39, s12
	v_lshl_add_u64 v[88:89], v[0:1], 0, v[66:67]
	v_lshl_add_u64 v[0:1], s[40:41], 0, v[72:73]
	v_lshl_add_u64 v[90:91], v[0:1], 0, v[66:67]
	v_lshl_add_u64 v[0:1], s[0:1], 0, v[74:75]
	s_lshl_b32 s0, s39, 8
	v_lshl_add_u64 v[92:93], v[0:1], 0, v[70:71]
	v_lshl_add_u64 v[0:1], s[40:41], 0, v[74:75]
	s_and_b32 s12, s0, 0x700
	v_readfirstlane_b32 s0, v97
	v_lshl_add_u64 v[94:95], v[0:1], 0, v[70:71]
	v_lshl_add_u64 v[0:1], v[80:81], 0, s[12:13]
	s_mov_b32 m0, s0
	v_readfirstlane_b32 s0, v105
	global_load_lds_dwordx4 v[0:1], off
	v_lshl_add_u64 v[0:1], v[82:83], 0, s[12:13]
	s_mov_b32 m0, s0
	v_readfirstlane_b32 s0, v106
	global_load_lds_dwordx4 v[0:1], off
	v_lshl_add_u64 v[0:1], v[84:85], 0, s[12:13]
	s_mov_b32 m0, s0
	v_readfirstlane_b32 s0, v107
	global_load_lds_dwordx4 v[0:1], off
	v_lshl_add_u64 v[0:1], v[86:87], 0, s[12:13]
	s_mov_b32 m0, s0
	v_readfirstlane_b32 s0, v108
	global_load_lds_dwordx4 v[0:1], off
	v_lshl_add_u64 v[0:1], v[88:89], 0, s[12:13]
	s_mov_b32 m0, s0
	v_readfirstlane_b32 s0, v109
	global_load_lds_dwordx4 v[0:1], off
	v_lshl_add_u64 v[0:1], v[90:91], 0, s[12:13]
	s_mov_b32 m0, s0
	v_readfirstlane_b32 s0, v110
	global_load_lds_dwordx4 v[0:1], off
	v_lshl_add_u64 v[0:1], v[92:93], 0, s[12:13]
	s_mov_b32 m0, s0
	v_readfirstlane_b32 s0, v111
	global_load_lds_dwordx4 v[0:1], off
	v_lshl_add_u64 v[0:1], v[94:95], 0, s[12:13]
	s_mov_b32 m0, s0
	s_lshl_b32 s0, s39, 7
	global_load_lds_dwordx4 v[0:1], off
	v_mov_b32_e32 v0, 0
	s_or_b32 s39, s0, 64
	s_mov_b32 s41, 0
	s_mov_b32 s40, 0
	v_mov_b32_e32 v1, v0
	v_mov_b32_e32 v2, v0
	v_mov_b32_e32 v3, v0
	v_mov_b32_e32 v4, v0
	v_mov_b32_e32 v5, v0
	v_mov_b32_e32 v6, v0
	v_mov_b32_e32 v7, v0
	v_mov_b32_e32 v8, v0
	v_mov_b32_e32 v9, v0
	v_mov_b32_e32 v10, v0
	v_mov_b32_e32 v11, v0
	v_mov_b32_e32 v12, v0
	v_mov_b32_e32 v13, v0
	v_mov_b32_e32 v14, v0
	v_mov_b32_e32 v15, v0
	v_mov_b32_e32 v16, v0
	v_mov_b32_e32 v17, v0
	v_mov_b32_e32 v18, v0
	v_mov_b32_e32 v19, v0
	v_mov_b32_e32 v20, v0
	v_mov_b32_e32 v21, v0
	v_mov_b32_e32 v22, v0
	v_mov_b32_e32 v23, v0
	v_mov_b32_e32 v24, v0
	v_mov_b32_e32 v25, v0
	v_mov_b32_e32 v26, v0
	v_mov_b32_e32 v27, v0
	v_mov_b32_e32 v28, v0
	v_mov_b32_e32 v29, v0
	v_mov_b32_e32 v30, v0
	v_mov_b32_e32 v31, v0
	v_mov_b32_e32 v32, v0
	v_mov_b32_e32 v33, v0
	v_mov_b32_e32 v34, v0
	v_mov_b32_e32 v35, v0
	v_mov_b32_e32 v36, v0
	v_mov_b32_e32 v37, v0
	v_mov_b32_e32 v38, v0
	v_mov_b32_e32 v39, v0
	v_mov_b32_e32 v40, v0
	v_mov_b32_e32 v41, v0
	v_mov_b32_e32 v42, v0
	v_mov_b32_e32 v43, v0
	v_mov_b32_e32 v44, v0
	v_mov_b32_e32 v45, v0
	v_mov_b32_e32 v46, v0
	v_mov_b32_e32 v47, v0
	v_mov_b32_e32 v48, v0
	v_mov_b32_e32 v49, v0
	v_mov_b32_e32 v50, v0
	v_mov_b32_e32 v51, v0
	v_mov_b32_e32 v52, v0
	v_mov_b32_e32 v53, v0
	v_mov_b32_e32 v54, v0
	v_mov_b32_e32 v55, v0
	v_mov_b32_e32 v56, v0
	v_mov_b32_e32 v57, v0
	v_mov_b32_e32 v58, v0
	v_mov_b32_e32 v59, v0
	v_mov_b32_e32 v60, v0
	v_mov_b32_e32 v61, v0
	v_mov_b32_e32 v62, v0
	v_mov_b32_e32 v63, v0
	s_waitcnt vmcnt(0) lgkmcnt(0)
	s_barrier
	s_branch .LBB0_872

; template <bool SW>
; __device__ __forceinline__ void gemm_mainloop(const bf16_t* __restrict__ A, int lda, const bf16_t* __restrict__ Bt, int ldb, int K,
;                                               f32x16 (&acc)[2][2], char* lds, int kstart) {
;     ...
;   for (int i = 0; i < 4; ++i) {
;     const int row = lrow + 8 * i; const int ch = (lane & 7) ^ ((row >> 1) & 7);
;     ap[i] = A + (size_t)row * lda + ch * 8; bp[i] = Bt + (size_t)row * ldb + ch * 8;
;   }
;   char* ldst = lds + (wid * 32) * 128 + lane * 16;
; #pragma unroll
;   for (int i = 0; i < 4; ++i) { glds16(ap[i] + kstart * 64, ldst + i * 1024); glds16(bp[i] + kstart * 64, ldst + 16384 + i * 1024); }
;   asm volatile("s_waitcnt vmcnt(0)" ::: "memory");
;   __syncthreads();
; __device__ void phase_peer_q(const Params& p, char* lds) {
;     ...
;     int mt, nt; if (!tile_at(260, 8, it, mt, nt)) break;
;     const int m0 = mt * 128, n0 = nt * 128;
;     f32x16 acc[2][2]; zero_acc(acc);
;     gemm_mainloop<true>((const bf16_t*)(ws + W_C) + (size_t)m0 * LDH, LDH, (const bf16_t*)(ws + W_WQ) + (size_t)n0 * LDH, LDH, 1024, acc, lds, 2 * ((mt + nt) & 7));
.LBB0_1019:
	s_lshr_b32 s1, s0, 3
	s_and_b32 s1, s1, 0xffffff8
	s_sub_i32 s3, s18, s1
	s_min_i32 s3, s3, 8
	s_abs_i32 s14, s3
	v_cvt_f32_u32_e32 v0, s14
	s_sub_i32 s39, 0, s14
	s_lshl_b32 s25, s1, 3
	s_sub_i32 s0, s0, s25
	v_rcp_iflag_f32_e32 v0, v0
	s_abs_i32 s38, s0
	s_xor_b32 s25, s0, s3
	s_add_i32 s1, s1, s17
	v_mul_f32_e32 v0, 0x4f7ffffe, v0
	v_cvt_u32_f32_e32 v0, v0
	s_ashr_i32 s25, s25, 31
	v_mov_b32_e32 v69, v65
	v_mov_b32_e32 v73, v65
	v_readfirstlane_b32 s40, v0
	s_mul_i32 s39, s39, s40
	s_mul_hi_u32 s39, s40, s39
	s_add_i32 s40, s40, s39
	s_mul_hi_u32 s39, s38, s40
	s_mul_i32 s40, s39, s14
	s_sub_i32 s38, s38, s40
	s_add_i32 s41, s39, 1
	s_sub_i32 s40, s38, s14
	s_cmp_ge_u32 s38, s14
	s_cselect_b32 s39, s41, s39
	s_cselect_b32 s38, s40, s38
	s_add_i32 s40, s39, 1
	s_cmp_ge_u32 s38, s14
	s_cselect_b32 s14, s40, s39
	s_xor_b32 s14, s14, s25
	s_sub_i32 s14, s14, s25
	s_mul_i32 s3, s14, s3
	s_sub_i32 s0, s0, s3
	s_add_i32 s40, s1, s0
	s_lshl_b32 s3, s40, 7
	s_lshl_b32 s25, s14, 7
	s_mul_i32 s0, s40, 0x44000
	s_mul_hi_i32 s1, s3, 0x880
	s_add_u32 s0, s20, s0
	s_addc_u32 s1, s21, s1
	s_mul_i32 s38, s14, 0x44000
	s_mul_hi_i32 s39, s25, 0x880
	s_add_u32 s38, s33, s38
	s_addc_u32 s39, s22, s39
	v_lshl_add_u64 v[0:1], s[0:1], 0, v[64:65]
	v_lshl_add_u64 v[82:83], v[0:1], 0, v[68:69]
	v_lshl_add_u64 v[0:1], s[38:39], 0, v[64:65]
	v_lshl_add_u64 v[84:85], v[0:1], 0, v[68:69]
	v_lshl_add_u64 v[0:1], s[0:1], 0, v[70:71]
	v_lshl_add_u64 v[86:87], v[0:1], 0, v[72:73]
	v_lshl_add_u64 v[0:1], s[38:39], 0, v[70:71]
	v_lshl_add_u64 v[88:89], v[0:1], 0, v[72:73]
	v_lshl_add_u64 v[0:1], s[0:1], 0, v[74:75]
	s_add_i32 s40, s40, s14
	v_lshl_add_u64 v[90:91], v[0:1], 0, v[68:69]
	v_lshl_add_u64 v[0:1], s[38:39], 0, v[74:75]
	v_lshl_add_u64 v[92:93], v[0:1], 0, v[68:69]
	v_lshl_add_u64 v[0:1], s[0:1], 0, v[76:77]
	s_lshl_b32 s0, s40, 8
	v_lshl_add_u64 v[94:95], v[0:1], 0, v[72:73]
	v_lshl_add_u64 v[0:1], s[38:39], 0, v[76:77]
	s_and_b32 s14, s0, 0x700
	v_readfirstlane_b32 s0, v99
	v_lshl_add_u64 v[96:97], v[0:1], 0, v[72:73]
	v_lshl_add_u64 v[0:1], v[82:83], 0, s[14:15]
	s_mov_b32 m0, s0
	v_readfirstlane_b32 s0, v106
	global_load_lds_dwordx4 v[0:1], off
	v_lshl_add_u64 v[0:1], v[84:85], 0, s[14:15]
	s_mov_b32 m0, s0
	v_readfirstlane_b32 s0, v107
	global_load_lds_dwordx4 v[0:1], off
	v_lshl_add_u64 v[0:1], v[86:87], 0, s[14:15]
	s_mov_b32 m0, s0
	v_readfirstlane_b32 s0, v108
	global_load_lds_dwordx4 v[0:1], off
	v_lshl_add_u64 v[0:1], v[88:89], 0, s[14:15]
	s_mov_b32 m0, s0
	v_readfirstlane_b32 s0, v109
	global_load_lds_dwordx4 v[0:1], off
	v_lshl_add_u64 v[0:1], v[90:91], 0, s[14:15]
	s_mov_b32 m0, s0
	v_readfirstlane_b32 s0, v110
	global_load_lds_dwordx4 v[0:1], off
	v_lshl_add_u64 v[0:1], v[92:93], 0, s[14:15]
	s_mov_b32 m0, s0
	v_readfirstlane_b32 s0, v111
	global_load_lds_dwordx4 v[0:1], off
	v_lshl_add_u64 v[0:1], v[94:95], 0, s[14:15]
	s_mov_b32 m0, s0
	v_readfirstlane_b32 s0, v112
	global_load_lds_dwordx4 v[0:1], off
	v_lshl_add_u64 v[0:1], v[96:97], 0, s[14:15]
	s_mov_b32 m0, s0
	s_lshl_b32 s0, s40, 7
	global_load_lds_dwordx4 v[0:1], off
	v_mov_b32_e32 v0, 0
	s_or_b32 s38, s0, 64
	s_mov_b32 s40, 0
	s_mov_b32 s39, 0
	v_mov_b32_e32 v1, v0
	v_mov_b32_e32 v2, v0
	v_mov_b32_e32 v3, v0
	v_mov_b32_e32 v4, v0
	v_mov_b32_e32 v5, v0
	v_mov_b32_e32 v6, v0
	v_mov_b32_e32 v7, v0
	v_mov_b32_e32 v8, v0
	v_mov_b32_e32 v9, v0
	v_mov_b32_e32 v10, v0
	v_mov_b32_e32 v11, v0
	v_mov_b32_e32 v12, v0
	v_mov_b32_e32 v13, v0
	v_mov_b32_e32 v14, v0
	v_mov_b32_e32 v15, v0
	v_mov_b32_e32 v16, v0
	v_mov_b32_e32 v17, v0
	v_mov_b32_e32 v18, v0
	v_mov_b32_e32 v19, v0
	v_mov_b32_e32 v20, v0
	v_mov_b32_e32 v21, v0
	v_mov_b32_e32 v22, v0
	v_mov_b32_e32 v23, v0
	v_mov_b32_e32 v24, v0
	v_mov_b32_e32 v25, v0
	v_mov_b32_e32 v26, v0
	v_mov_b32_e32 v27, v0
	v_mov_b32_e32 v28, v0
	v_mov_b32_e32 v29, v0
	v_mov_b32_e32 v30, v0
	v_mov_b32_e32 v31, v0
	v_mov_b32_e32 v32, v0
	v_mov_b32_e32 v33, v0
	v_mov_b32_e32 v34, v0
	v_mov_b32_e32 v35, v0
	v_mov_b32_e32 v36, v0
	v_mov_b32_e32 v37, v0
	v_mov_b32_e32 v38, v0
	v_mov_b32_e32 v39, v0
	v_mov_b32_e32 v40, v0
	v_mov_b32_e32 v41, v0
	v_mov_b32_e32 v42, v0
	v_mov_b32_e32 v43, v0
	v_mov_b32_e32 v44, v0
	v_mov_b32_e32 v45, v0
	v_mov_b32_e32 v46, v0
	v_mov_b32_e32 v47, v0
	v_mov_b32_e32 v48, v0
	v_mov_b32_e32 v49, v0
	v_mov_b32_e32 v50, v0
	v_mov_b32_e32 v51, v0
	v_mov_b32_e32 v52, v0
	v_mov_b32_e32 v53, v0
	v_mov_b32_e32 v54, v0
	v_mov_b32_e32 v55, v0
	v_mov_b32_e32 v56, v0
	v_mov_b32_e32 v57, v0
	v_mov_b32_e32 v58, v0
	v_mov_b32_e32 v59, v0
	v_mov_b32_e32 v60, v0
	v_mov_b32_e32 v61, v0
	v_mov_b32_e32 v62, v0
	v_mov_b32_e32 v63, v0
	s_waitcnt vmcnt(0) lgkmcnt(0)
	s_barrier
	s_branch .LBB0_1021
